# same as previous, gMLP rebalance bookkeeping kept in dead SGPRs instead of s100/s101
# baseline (speedup 1.0000x reference)
.LBB0_600:
	s_and_b64 vcc, exec, s[0:1]
	s_cbranch_vccz .LBB0_605
	v_readlane_b32 s2, v253, 11
	s_nop 0
	s_cmp_lt_u32 s2, 4
	s_cbranch_scc1 .LBB0_605

.LBB0_604:
	v_readlane_b32 s4, v255, 29
	s_add_u32 s4, s0, s4
	v_or_b32_e32 v82, s10, v37
	s_addc_u32 s5, s1, 0
	v_lshlrev_b32_e32 v194, 4, v47
	v_or_b32_e32 v2, s3, v82
	v_lshl_add_u64 v[0:1], s[4:5], 0, v[194:195]
	s_mov_b64 s[4:5], 0x90a0000
	v_ashrrev_i32_e32 v3, 31, v2
	v_lshl_add_u64 v[76:77], v[0:1], 0, s[4:5]
	v_lshlrev_b64 v[2:3], 8, v[2:3]
	v_mov_b32_e32 v0, v192
	v_mov_b32_e32 v6, v192
	v_mov_b32_e32 v10, v192
	v_mov_b32_e32 v14, v192
	v_mov_b32_e32 v18, v192
	v_mov_b32_e32 v22, v192
	v_mov_b32_e32 v26, v192
	v_mov_b32_e32 v30, v192
	v_lshl_add_u64 v[2:3], v[76:77], 0, v[2:3]
	s_waitcnt vmcnt(0) lgkmcnt(0)
	s_barrier
	global_load_dwordx4 v[32:35], v[2:3], off
	v_or_b32_e32 v4, s2, v82
	v_ashrrev_i32_e32 v5, 31, v4
	v_lshlrev_b64 v[4:5], 8, v[4:5]
	v_lshl_add_u64 v[4:5], v[76:77], 0, v[4:5]
	global_load_dwordx4 v[78:81], v[4:5], off
	global_load_dwordx4 v[90:93], v[2:3], off offset:64
	v_or_b32_e32 v1, s8, v37
	s_movk_i32 s4, 0x108
	v_and_b32_e32 v2, 48, v57
	v_mul_lo_u32 v1, v1, s4
	v_add3_u32 v57, 0, v2, v1
	ds_read2_b64 v[86:89], v57 offset1:1
	v_mov_b32_e32 v1, v0
	v_add_u32_e32 v83, 0x1080, v57
	v_mov_b32_e32 v2, v0
	v_mov_b32_e32 v3, v0
	v_add_u32_e32 v84, 0x2100, v57
	v_add_u32_e32 v85, 0x3180, v57
	ds_read2_b64 v[94:97], v83 offset1:1
	ds_read2_b64 v[98:101], v84 offset1:1
	v_mov_b32_e32 v7, v6
	v_mov_b32_e32 v8, v6
	v_mov_b32_e32 v9, v6
	v_mov_b32_e32 v11, v10
	v_mov_b32_e32 v12, v10
	v_mov_b32_e32 v13, v10
	v_mov_b32_e32 v15, v14
	v_mov_b32_e32 v16, v14
	v_mov_b32_e32 v17, v14
	v_mov_b32_e32 v19, v18
	v_mov_b32_e32 v20, v18
	v_mov_b32_e32 v21, v18
	v_mov_b32_e32 v23, v22
	v_mov_b32_e32 v24, v22
	v_mov_b32_e32 v25, v22
	v_mov_b32_e32 v27, v26
	v_mov_b32_e32 v28, v26
	v_mov_b32_e32 v29, v26
	v_mov_b32_e32 v31, v30
	v_readlane_b32 s4, v253, 36
	s_waitcnt vmcnt(0) lgkmcnt(0)
	v_mfma_f32_16x16x32_bf16 v[110:113], v[86:89], v[78:81], v[18:21]
	v_or_b32_e32 v37, s4, v37
	s_mov_b64 s[4:5], 0x2040600
	v_mfma_f32_16x16x32_bf16 v[102:105], v[86:89], v[32:35], v[0:3]
	v_add_u32_e32 v86, 0x10c0, v57
	v_add_u32_e32 v87, 0x2140, v57
	v_add_u32_e32 v88, 0x31c0, v57
	ds_read2_b64 v[0:3], v85 offset1:1
	v_mfma_f32_16x16x32_bf16 v[6:9], v[94:97], v[32:35], v[6:9]
	ds_read2_b64 v[114:117], v87 offset1:1
	v_mfma_f32_16x16x32_bf16 v[10:13], v[98:101], v[32:35], v[10:13]
	s_waitcnt lgkmcnt(1)
	v_mfma_f32_16x16x32_bf16 v[14:17], v[0:3], v[32:35], v[14:17]
	v_mov_b32_e32 v32, v30
	v_mov_b32_e32 v33, v30
	v_mfma_f32_16x16x32_bf16 v[94:97], v[94:97], v[78:81], v[22:25]
	v_mfma_f32_16x16x32_bf16 v[98:101], v[98:101], v[78:81], v[26:29]
	v_mfma_f32_16x16x32_bf16 v[0:3], v[0:3], v[78:81], v[30:33]
	ds_read2_b64 v[78:81], v57 offset0:8 offset1:9
	s_waitcnt lgkmcnt(0)
	v_mfma_f32_16x16x32_bf16 v[28:31], v[78:81], v[90:93], v[102:105]
	s_nop 2
	ds_read2_b64 v[102:105], v86 offset1:1
	ds_read2_b64 v[32:35], v88 offset1:1
	s_waitcnt lgkmcnt(1)
	v_mfma_f32_16x16x32_bf16 v[24:27], v[102:105], v[90:93], v[6:9]
	v_mfma_f32_16x16x32_bf16 v[20:23], v[114:117], v[90:93], v[10:13]
	s_waitcnt lgkmcnt(0)
	v_mfma_f32_16x16x32_bf16 v[12:15], v[32:35], v[90:93], v[14:17]
	global_load_dwordx4 v[90:93], v[4:5], off offset:64
	v_lshlrev_b32_e32 v4, 2, v47
	s_waitcnt vmcnt(0) lgkmcnt(0)
	v_mfma_f32_16x16x32_bf16 v[8:11], v[102:105], v[90:93], v[94:97]
	s_nop 2
	v_lshlrev_b32_e32 v94, 16, v74
	v_mul_f32_e32 v47, 0x3d372713, v94
	v_mul_f32_e32 v47, v47, v94
	v_mov_b32_e32 v67, v94
	v_fmac_f32_e32 v67, v47, v67
	v_mul_f32_e32 v47, 0x3f4c422a, v67
	v_add_f32_e32 v47, v47, v47
	v_and_b32_e32 v95, 0xffff0000, v74
	v_mul_f32_e32 v47, 0xbfb8aa3b, v47
	v_mfma_f32_16x16x32_bf16 v[16:19], v[78:81], v[90:93], v[110:113]
	v_exp_f32_e32 v80, v47
	v_mul_f32_e32 v47, 0x3d372713, v95
	v_mul_f32_e32 v47, v47, v95
	v_mov_b32_e32 v67, v95
	v_fmac_f32_e32 v67, v47, v67
	v_mul_f32_e32 v47, 0x3f4c422a, v67
	v_add_f32_e32 v47, v47, v47
	v_mul_f32_e32 v47, 0xbfb8aa3b, v47
	v_exp_f32_e32 v81, v47
	v_mfma_f32_16x16x32_bf16 v[0:3], v[32:35], v[90:93], v[0:3]
	v_mov_b64_e32 v[32:33], s[0:1]
	v_or_b32_e32 v47, s3, v37
	v_pk_add_f32 v[34:35], v[80:81], 1.0 op_sel_hi:[1,0]
	v_mad_i64_i32 v[80:81], s[0:1], v47, s86, v[32:33]
	v_or_b32_e32 v78, s8, v4
	v_mfma_f32_16x16x32_bf16 v[4:7], v[114:117], v[90:93], v[98:101]
	v_lshl_add_u64 v[80:81], v[80:81], 0, s[4:5]
	v_rcp_f32_e32 v35, v35
	v_pk_add_f32 v[16:17], v[56:57], v[16:17] op_sel_hi:[0,1]
	v_lshlrev_b32_e32 v74, 16, v75
	v_mul_f32_e32 v67, 0x3d372713, v74
	v_mul_f32_e32 v67, v67, v74
	v_mov_b32_e32 v90, v74
	v_fmac_f32_e32 v90, v67, v90
	v_mul_f32_e32 v67, 0x3f4c422a, v90
	v_add_f32_e32 v67, v67, v67
	v_and_b32_e32 v75, 0xffff0000, v75
	v_mul_f32_e32 v67, 0xbfb8aa3b, v67
	v_exp_f32_e32 v90, v67
	v_mul_f32_e32 v67, 0x3d372713, v75
	v_mul_f32_e32 v67, v67, v75
	v_mov_b32_e32 v91, v75
	v_fmac_f32_e32 v91, v67, v91
	v_mul_f32_e32 v67, 0x3f4c422a, v91
	v_add_f32_e32 v67, v67, v67
	v_mul_f32_e32 v67, 0xbfb8aa3b, v67
	v_exp_f32_e32 v91, v67
	v_rcp_f32_e32 v34, v34
	s_nop 0
	v_pk_mul_f32 v[34:35], v[34:35], v[94:95]
	v_pk_add_f32 v[90:91], v[90:91], 1.0 op_sel_hi:[1,0]
	v_pk_add_f32 v[18:19], v[56:57], v[18:19] op_sel_hi:[0,1]
	v_pk_add_f32 v[8:9], v[56:57], v[8:9] op_sel_hi:[0,1]
	v_pk_add_f32 v[10:11], v[56:57], v[10:11] op_sel_hi:[0,1]
	v_pk_add_f32 v[4:5], v[56:57], v[4:5] op_sel_hi:[0,1]
	v_pk_add_f32 v[28:29], v[66:67], v[28:29] op_sel_hi:[0,1]
	v_pk_mul_f32 v[28:29], v[34:35], v[28:29]
	v_rcp_f32_e32 v35, v91
	v_pk_add_f32 v[6:7], v[56:57], v[6:7] op_sel_hi:[0,1]
	v_rcp_f32_e32 v34, v90
	s_nop 0
	v_pk_mul_f32 v[34:35], v[34:35], v[74:75]
	v_pk_add_f32 v[30:31], v[66:67], v[30:31] op_sel_hi:[0,1]
	v_pk_mul_f32 v[30:31], v[34:35], v[30:31]
	v_lshlrev_b32_e32 v34, 16, v72
	v_mul_f32_e32 v47, 0x3d372713, v34
	v_mul_f32_e32 v47, v47, v34
	v_mov_b32_e32 v67, v34
	v_fmac_f32_e32 v67, v47, v67
	v_mul_f32_e32 v47, 0x3f4c422a, v67
	v_add_f32_e32 v47, v47, v47
	v_and_b32_e32 v35, 0xffff0000, v72
	v_mul_f32_e32 v47, 0xbfb8aa3b, v47
	v_exp_f32_e32 v74, v47
	v_mul_f32_e32 v47, 0x3d372713, v35
	v_mul_f32_e32 v47, v47, v35
	v_mov_b32_e32 v67, v35
	v_fmac_f32_e32 v67, v47, v67
	v_mul_f32_e32 v47, 0x3f4c422a, v67
	v_add_f32_e32 v47, v47, v47
	v_mul_f32_e32 v47, 0xbfb8aa3b, v47
	v_exp_f32_e32 v75, v47
	v_cvt_pk_bf16_f32 v91, v30, v31
	v_ashrrev_i32_e32 v79, 31, v78
	v_cvt_pk_bf16_f32 v90, v28, v29
	v_pk_add_f32 v[30:31], v[74:75], 1.0 op_sel_hi:[1,0]
	v_lshlrev_b64 v[28:29], 1, v[78:79]
	v_lshl_add_u64 v[74:75], v[80:81], 0, v[28:29]
	global_store_dwordx2 v[74:75], v[90:91], off
	v_pk_add_f32 v[0:1], v[56:57], v[0:1] op_sel_hi:[0,1]
	v_rcp_f32_e32 v31, v31
	v_pk_add_f32 v[2:3], v[56:57], v[2:3] op_sel_hi:[0,1]
	v_lshlrev_b32_e32 v72, 16, v73
	v_mul_f32_e32 v74, 0x3d372713, v72
	v_mul_f32_e32 v74, v74, v72
	v_mov_b32_e32 v75, v72
	v_and_b32_e32 v73, 0xffff0000, v73
	v_fmac_f32_e32 v75, v74, v75
	v_mul_f32_e32 v74, 0x3f4c422a, v75
	v_mul_f32_e32 v75, 0x3d372713, v73
	v_mul_f32_e32 v75, v75, v73
	v_mov_b32_e32 v89, v73
	v_fmac_f32_e32 v89, v75, v89
	v_mul_f32_e32 v75, 0x3f4c422a, v89
	v_add_f32_e32 v74, v74, v74
	v_add_f32_e32 v75, v75, v75
	v_mul_f32_e32 v74, 0xbfb8aa3b, v74
	v_mul_f32_e32 v75, 0xbfb8aa3b, v75
	v_exp_f32_e32 v74, v74
	v_exp_f32_e32 v75, v75
	v_rcp_f32_e32 v30, v30
	s_nop 0
	v_pk_mul_f32 v[30:31], v[30:31], v[34:35]
	v_pk_add_f32 v[74:75], v[74:75], 1.0 op_sel_hi:[1,0]
	s_nop 0
	v_pk_add_f32 v[24:25], v[66:67], v[24:25] op_sel_hi:[0,1]
	v_pk_mul_f32 v[24:25], v[30:31], v[24:25]
	v_rcp_f32_e32 v31, v75
	v_rcp_f32_e32 v30, v74
	s_nop 0
	v_pk_mul_f32 v[30:31], v[30:31], v[72:73]
	v_pk_add_f32 v[26:27], v[66:67], v[26:27] op_sel_hi:[0,1]
	v_lshlrev_b32_e32 v34, 16, v70
	v_pk_mul_f32 v[26:27], v[30:31], v[26:27]
	v_mul_f32_e32 v31, 0x3d372713, v34
	v_mul_f32_e32 v31, v31, v34
	v_mov_b32_e32 v47, v34
	v_fmac_f32_e32 v47, v31, v47
	v_mul_f32_e32 v31, 0x3f4c422a, v47
	v_add_f32_e32 v31, v31, v31
	v_and_b32_e32 v35, 0xffff0000, v70
	v_mul_f32_e32 v31, 0xbfb8aa3b, v31
	v_exp_f32_e32 v72, v31
	v_mul_f32_e32 v31, 0x3d372713, v35
	v_mul_f32_e32 v31, v31, v35
	v_mov_b32_e32 v47, v35
	v_fmac_f32_e32 v47, v31, v47
	v_mul_f32_e32 v31, 0x3f4c422a, v47
	v_add_f32_e32 v31, v31, v31
	v_mul_f32_e32 v31, 0xbfb8aa3b, v31
	v_exp_f32_e32 v73, v31
	v_cvt_pk_bf16_f32 v24, v24, v25
	v_cvt_pk_bf16_f32 v25, v26, v27
	v_or_b32_e32 v30, 16, v78
	v_pk_add_f32 v[26:27], v[72:73], 1.0 op_sel_hi:[1,0]
	v_ashrrev_i32_e32 v31, 31, v30
	v_lshlrev_b64 v[30:31], 1, v[30:31]
	v_lshl_add_u64 v[72:73], v[80:81], 0, v[30:31]
	global_store_dwordx2 v[72:73], v[24:25], off
	v_rcp_f32_e32 v25, v27
	v_lshlrev_b32_e32 v70, 16, v71
	v_mul_f32_e32 v47, 0x3d372713, v70
	v_mul_f32_e32 v47, v47, v70
	v_mov_b32_e32 v67, v70
	v_fmac_f32_e32 v67, v47, v67
	v_mul_f32_e32 v47, 0x3f4c422a, v67
	v_add_f32_e32 v47, v47, v47
	v_and_b32_e32 v71, 0xffff0000, v71
	v_mul_f32_e32 v47, 0xbfb8aa3b, v47
	v_exp_f32_e32 v72, v47
	v_mul_f32_e32 v47, 0x3d372713, v71
	v_mul_f32_e32 v47, v47, v71
	v_mov_b32_e32 v67, v71
	v_fmac_f32_e32 v67, v47, v67
	v_mul_f32_e32 v47, 0x3f4c422a, v67
	v_add_f32_e32 v47, v47, v47
	v_mul_f32_e32 v47, 0xbfb8aa3b, v47
	v_exp_f32_e32 v73, v47
	v_rcp_f32_e32 v24, v26
	s_nop 0
	v_pk_mul_f32 v[24:25], v[24:25], v[34:35]
	v_pk_add_f32 v[26:27], v[72:73], 1.0 op_sel_hi:[1,0]
	s_nop 0
	v_pk_add_f32 v[20:21], v[66:67], v[20:21] op_sel_hi:[0,1]
	v_pk_mul_f32 v[20:21], v[24:25], v[20:21]
	v_rcp_f32_e32 v25, v27
	v_rcp_f32_e32 v24, v26
	s_nop 0
	v_pk_mul_f32 v[24:25], v[24:25], v[70:71]
	v_pk_add_f32 v[22:23], v[66:67], v[22:23] op_sel_hi:[0,1]
	v_lshlrev_b32_e32 v26, 16, v68
	v_pk_mul_f32 v[22:23], v[24:25], v[22:23]
	v_mul_f32_e32 v25, 0x3d372713, v26
	v_mul_f32_e32 v25, v25, v26
	v_mov_b32_e32 v34, v26
	v_fmac_f32_e32 v34, v25, v34
	v_mul_f32_e32 v25, 0x3f4c422a, v34
	v_add_f32_e32 v25, v25, v25
	v_and_b32_e32 v27, 0xffff0000, v68
	v_mul_f32_e32 v25, 0xbfb8aa3b, v25
	v_exp_f32_e32 v34, v25
	v_mul_f32_e32 v25, 0x3d372713, v27
	v_mul_f32_e32 v25, v25, v27
	v_mov_b32_e32 v35, v27
	v_fmac_f32_e32 v35, v25, v35
	v_mul_f32_e32 v25, 0x3f4c422a, v35
	v_add_f32_e32 v25, v25, v25
	v_mul_f32_e32 v25, 0xbfb8aa3b, v25
	v_exp_f32_e32 v35, v25
	v_cvt_pk_bf16_f32 v20, v20, v21
	v_cvt_pk_bf16_f32 v21, v22, v23
	v_or_b32_e32 v24, 32, v78
	v_pk_add_f32 v[22:23], v[34:35], 1.0 op_sel_hi:[1,0]
	v_ashrrev_i32_e32 v25, 31, v24
	v_lshlrev_b64 v[34:35], 1, v[24:25]
	v_lshl_add_u64 v[24:25], v[80:81], 0, v[34:35]
	global_store_dwordx2 v[24:25], v[20:21], off
	v_rcp_f32_e32 v21, v23
	v_lshlrev_b32_e32 v24, 16, v69
	v_mul_f32_e32 v67, 0x3d372713, v24
	v_mul_f32_e32 v67, v67, v24
	v_mov_b32_e32 v68, v24
	v_fmac_f32_e32 v68, v67, v68
	v_mul_f32_e32 v67, 0x3f4c422a, v68
	v_add_f32_e32 v67, v67, v67
	v_and_b32_e32 v25, 0xffff0000, v69
	v_mul_f32_e32 v67, 0xbfb8aa3b, v67
	v_exp_f32_e32 v68, v67
	v_mul_f32_e32 v67, 0x3d372713, v25
	v_mul_f32_e32 v67, v67, v25
	v_mov_b32_e32 v69, v25
	v_fmac_f32_e32 v69, v67, v69
	v_mul_f32_e32 v67, 0x3f4c422a, v69
	v_add_f32_e32 v67, v67, v67
	v_mul_f32_e32 v67, 0xbfb8aa3b, v67
	v_exp_f32_e32 v69, v67
	v_rcp_f32_e32 v20, v22
	s_nop 0
	v_pk_mul_f32 v[20:21], v[20:21], v[26:27]
	v_pk_add_f32 v[22:23], v[68:69], 1.0 op_sel_hi:[1,0]
	s_nop 0
	v_pk_add_f32 v[12:13], v[66:67], v[12:13] op_sel_hi:[0,1]
	v_pk_mul_f32 v[12:13], v[20:21], v[12:13]
	v_rcp_f32_e32 v21, v23
	v_rcp_f32_e32 v20, v22
	s_nop 0
	v_pk_mul_f32 v[20:21], v[20:21], v[24:25]
	v_pk_add_f32 v[14:15], v[66:67], v[14:15] op_sel_hi:[0,1]
	v_pk_mul_f32 v[14:15], v[20:21], v[14:15]
	v_or_b32_e32 v20, 48, v78
	v_cvt_pk_bf16_f32 v12, v12, v13
	v_cvt_pk_bf16_f32 v13, v14, v15
	v_ashrrev_i32_e32 v21, 31, v20
	v_lshlrev_b32_e32 v14, 16, v64
	v_lshlrev_b64 v[66:67], 1, v[20:21]
	v_mul_f32_e32 v20, 0x3d372713, v14
	v_mul_f32_e32 v20, v20, v14
	v_mov_b32_e32 v21, v14
	v_and_b32_e32 v15, 0xffff0000, v64
	v_fmac_f32_e32 v21, v20, v21
	v_mul_f32_e32 v20, 0x3f4c422a, v21
	v_mul_f32_e32 v21, 0x3d372713, v15
	v_mul_f32_e32 v21, v21, v15
	v_mov_b32_e32 v22, v15
	v_fmac_f32_e32 v22, v21, v22
	v_mul_f32_e32 v21, 0x3f4c422a, v22
	v_add_f32_e32 v20, v20, v20
	v_add_f32_e32 v21, v21, v21
	v_mul_f32_e32 v20, 0xbfb8aa3b, v20
	v_mul_f32_e32 v21, 0xbfb8aa3b, v21
	v_exp_f32_e32 v20, v20
	v_exp_f32_e32 v21, v21
	v_lshl_add_u64 v[22:23], v[80:81], 0, v[66:67]
	global_store_dwordx2 v[22:23], v[12:13], off
	v_or_b32_e32 v12, s2, v37
	v_pk_add_f32 v[20:21], v[20:21], 1.0 op_sel_hi:[1,0]
	v_mad_i64_i32 v[12:13], s[0:1], v12, s86, v[32:33]
	v_lshl_add_u64 v[12:13], v[12:13], 0, s[4:5]
	v_or_b32_e32 v37, 64, v37
	v_rcp_f32_e32 v21, v21
	v_lshlrev_b32_e32 v22, 16, v65
	v_mul_f32_e32 v24, 0x3d372713, v22
	v_mul_f32_e32 v24, v24, v22
	v_mov_b32_e32 v25, v22
	v_and_b32_e32 v23, 0xffff0000, v65
	v_fmac_f32_e32 v25, v24, v25
	v_mul_f32_e32 v24, 0x3f4c422a, v25
	v_mul_f32_e32 v25, 0x3d372713, v23
	v_mul_f32_e32 v25, v25, v23
	v_mov_b32_e32 v64, v23
	v_fmac_f32_e32 v64, v25, v64
	v_mul_f32_e32 v25, 0x3f4c422a, v64
	v_add_f32_e32 v24, v24, v24
	v_add_f32_e32 v25, v25, v25
	v_mul_f32_e32 v24, 0xbfb8aa3b, v24
	v_mul_f32_e32 v25, 0xbfb8aa3b, v25
	v_exp_f32_e32 v24, v24
	v_exp_f32_e32 v25, v25
	v_rcp_f32_e32 v20, v20
	s_nop 0
	v_pk_mul_f32 v[14:15], v[20:21], v[14:15]
	v_pk_add_f32 v[24:25], v[24:25], 1.0 op_sel_hi:[1,0]
	v_pk_mul_f32 v[14:15], v[14:15], v[16:17]
	s_nop 0
	v_cvt_pk_bf16_f32 v14, v14, v15
	v_add_u32_e32 v47, 0x1100, v57
	v_rcp_f32_e32 v17, v25
	v_rcp_f32_e32 v16, v24
	v_lshlrev_b32_e32 v20, 16, v62
	v_pk_mul_f32 v[16:17], v[16:17], v[22:23]
	v_mul_f32_e32 v22, 0x3d372713, v20
	v_mul_f32_e32 v22, v22, v20
	v_mov_b32_e32 v23, v20
	v_and_b32_e32 v21, 0xffff0000, v62
	v_fmac_f32_e32 v23, v22, v23
	v_mul_f32_e32 v22, 0x3f4c422a, v23
	v_mul_f32_e32 v23, 0x3d372713, v21
	v_mul_f32_e32 v23, v23, v21
	v_mov_b32_e32 v24, v21
	v_fmac_f32_e32 v24, v23, v24
	v_mul_f32_e32 v23, 0x3f4c422a, v24
	v_add_f32_e32 v22, v22, v22
	v_add_f32_e32 v23, v23, v23
	v_mul_f32_e32 v22, 0xbfb8aa3b, v22
	v_mul_f32_e32 v23, 0xbfb8aa3b, v23
	v_exp_f32_e32 v22, v22
	v_exp_f32_e32 v23, v23
	v_pk_mul_f32 v[16:17], v[16:17], v[18:19]
	v_mov_b32_e32 v62, v195
	v_cvt_pk_bf16_f32 v15, v16, v17
	v_pk_add_f32 v[18:19], v[22:23], 1.0 op_sel_hi:[1,0]
	v_lshl_add_u64 v[16:17], v[12:13], 0, v[28:29]
	global_store_dwordx2 v[16:17], v[14:15], off
	v_rcp_f32_e32 v15, v19
	v_lshlrev_b32_e32 v16, 16, v63
	v_mul_f32_e32 v22, 0x3d372713, v16
	v_mul_f32_e32 v22, v22, v16
	v_mov_b32_e32 v23, v16
	v_and_b32_e32 v17, 0xffff0000, v63
	v_fmac_f32_e32 v23, v22, v23
	v_mul_f32_e32 v22, 0x3f4c422a, v23
	v_mul_f32_e32 v23, 0x3d372713, v17
	v_mul_f32_e32 v23, v23, v17
	v_mov_b32_e32 v25, v17
	v_fmac_f32_e32 v25, v23, v25
	v_mul_f32_e32 v23, 0x3f4c422a, v25
	v_add_f32_e32 v22, v22, v22
	v_add_f32_e32 v23, v23, v23
	v_mul_f32_e32 v22, 0xbfb8aa3b, v22
	v_mul_f32_e32 v23, 0xbfb8aa3b, v23
	v_exp_f32_e32 v22, v22
	v_exp_f32_e32 v23, v23
	v_rcp_f32_e32 v14, v18
	s_nop 0
	v_pk_mul_f32 v[14:15], v[14:15], v[20:21]
	v_pk_add_f32 v[18:19], v[22:23], 1.0 op_sel_hi:[1,0]
	v_pk_mul_f32 v[8:9], v[14:15], v[8:9]
	s_nop 0
	v_cvt_pk_bf16_f32 v8, v8, v9
	v_mov_b32_e32 v24, v192
	v_rcp_f32_e32 v15, v19
	v_rcp_f32_e32 v14, v18
	s_nop 0
	v_pk_mul_f32 v[14:15], v[14:15], v[16:17]
	v_lshlrev_b32_e32 v16, 16, v60
	v_mul_f32_e32 v18, 0x3d372713, v16
	v_mul_f32_e32 v18, v18, v16
	v_mov_b32_e32 v19, v16
	v_and_b32_e32 v17, 0xffff0000, v60
	v_fmac_f32_e32 v19, v18, v19
	v_mul_f32_e32 v18, 0x3f4c422a, v19
	v_mul_f32_e32 v19, 0x3d372713, v17
	v_mul_f32_e32 v19, v19, v17
	v_mov_b32_e32 v20, v17
	v_fmac_f32_e32 v20, v19, v20
	v_mul_f32_e32 v19, 0x3f4c422a, v20
	v_add_f32_e32 v18, v18, v18
	v_add_f32_e32 v19, v19, v19
	v_mul_f32_e32 v18, 0xbfb8aa3b, v18
	v_mul_f32_e32 v19, 0xbfb8aa3b, v19
	v_exp_f32_e32 v18, v18
	v_exp_f32_e32 v19, v19
	v_pk_mul_f32 v[10:11], v[14:15], v[10:11]
	v_pk_add_f32 v[14:15], v[18:19], 1.0 op_sel_hi:[1,0]
	s_nop 0
	v_cvt_pk_bf16_f32 v9, v10, v11
	v_lshl_add_u64 v[10:11], v[12:13], 0, v[30:31]
	global_store_dwordx2 v[10:11], v[8:9], off
	v_rcp_f32_e32 v9, v15
	v_lshlrev_b32_e32 v10, 16, v61
	v_mul_f32_e32 v18, 0x3d372713, v10
	v_mul_f32_e32 v18, v18, v10
	v_mov_b32_e32 v19, v10
	v_and_b32_e32 v11, 0xffff0000, v61
	v_fmac_f32_e32 v19, v18, v19
	v_mul_f32_e32 v18, 0x3f4c422a, v19
	v_mul_f32_e32 v19, 0x3d372713, v11
	v_mul_f32_e32 v19, v19, v11
	v_mov_b32_e32 v21, v11
	v_fmac_f32_e32 v21, v19, v21
	v_mul_f32_e32 v19, 0x3f4c422a, v21
	v_add_f32_e32 v18, v18, v18
	v_add_f32_e32 v19, v19, v19
	v_mul_f32_e32 v18, 0xbfb8aa3b, v18
	v_mul_f32_e32 v19, 0xbfb8aa3b, v19
	v_exp_f32_e32 v18, v18
	v_exp_f32_e32 v19, v19
	v_rcp_f32_e32 v8, v14
	s_nop 0
	v_pk_mul_f32 v[8:9], v[8:9], v[16:17]
	v_pk_add_f32 v[14:15], v[18:19], 1.0 op_sel_hi:[1,0]
	v_pk_mul_f32 v[4:5], v[8:9], v[4:5]
	s_nop 0
	v_cvt_pk_bf16_f32 v4, v4, v5
	v_mov_b32_e32 v20, v192
	v_rcp_f32_e32 v9, v15
	v_rcp_f32_e32 v8, v14
	s_nop 0
	v_pk_mul_f32 v[8:9], v[8:9], v[10:11]
	v_lshlrev_b32_e32 v10, 16, v58
	v_mul_f32_e32 v14, 0x3d372713, v10
	v_mul_f32_e32 v14, v14, v10
	v_mov_b32_e32 v15, v10
	v_and_b32_e32 v11, 0xffff0000, v58
	v_fmac_f32_e32 v15, v14, v15
	v_mul_f32_e32 v14, 0x3f4c422a, v15
	v_mul_f32_e32 v15, 0x3d372713, v11
	v_mul_f32_e32 v15, v15, v11
	v_mov_b32_e32 v16, v11
	v_fmac_f32_e32 v16, v15, v16
	v_mul_f32_e32 v15, 0x3f4c422a, v16
	v_add_f32_e32 v14, v14, v14
	v_add_f32_e32 v15, v15, v15
	v_mul_f32_e32 v14, 0xbfb8aa3b, v14
	v_mul_f32_e32 v15, 0xbfb8aa3b, v15
	v_exp_f32_e32 v14, v14
	v_exp_f32_e32 v15, v15
	v_pk_mul_f32 v[6:7], v[8:9], v[6:7]
	v_mov_b32_e32 v58, v192
	v_cvt_pk_bf16_f32 v5, v6, v7
	v_pk_add_f32 v[8:9], v[14:15], 1.0 op_sel_hi:[1,0]
	v_lshl_add_u64 v[6:7], v[12:13], 0, v[34:35]
	global_store_dwordx2 v[6:7], v[4:5], off
	v_rcp_f32_e32 v5, v9
	v_lshlrev_b32_e32 v6, 16, v59
	v_mul_f32_e32 v14, 0x3d372713, v6
	v_mul_f32_e32 v14, v14, v6
	v_mov_b32_e32 v15, v6
	v_and_b32_e32 v7, 0xffff0000, v59
	v_fmac_f32_e32 v15, v14, v15
	v_mul_f32_e32 v14, 0x3f4c422a, v15
	v_mul_f32_e32 v15, 0x3d372713, v7
	v_mul_f32_e32 v15, v15, v7
	v_mov_b32_e32 v17, v7
	v_fmac_f32_e32 v17, v15, v17
	v_mul_f32_e32 v15, 0x3f4c422a, v17
	v_add_f32_e32 v14, v14, v14
	v_add_f32_e32 v15, v15, v15
	v_mul_f32_e32 v14, 0xbfb8aa3b, v14
	v_mul_f32_e32 v15, 0xbfb8aa3b, v15
	v_exp_f32_e32 v14, v14
	v_exp_f32_e32 v15, v15
	v_rcp_f32_e32 v4, v8
	s_nop 0
	v_pk_mul_f32 v[4:5], v[4:5], v[10:11]
	v_pk_add_f32 v[8:9], v[14:15], 1.0 op_sel_hi:[1,0]
	v_pk_mul_f32 v[0:1], v[4:5], v[0:1]
	s_nop 0
	v_cvt_pk_bf16_f32 v0, v0, v1
	v_mov_b32_e32 v16, v192
	v_rcp_f32_e32 v5, v9
	v_rcp_f32_e32 v4, v8
	s_nop 0
	v_pk_mul_f32 v[4:5], v[4:5], v[6:7]
	v_mov_b32_e32 v8, v192
	v_pk_mul_f32 v[2:3], v[4:5], v[2:3]
	v_or_b32_e32 v5, 64, v82
	v_cvt_pk_bf16_f32 v1, v2, v3
	v_lshl_add_u64 v[2:3], v[12:13], 0, v[66:67]
	global_store_dwordx2 v[2:3], v[0:1], off
	v_or_b32_e32 v0, s3, v5
	v_ashrrev_i32_e32 v1, 31, v0
	v_lshlrev_b64 v[0:1], 8, v[0:1]
	v_lshl_add_u64 v[2:3], v[76:77], 0, v[0:1]
	v_or_b32_e32 v0, s2, v5
	v_ashrrev_i32_e32 v1, 31, v0
	v_mov_b32_e32 v4, v192
	v_mov_b32_e32 v12, v192
	v_lshlrev_b64 v[0:1], 8, v[0:1]
	global_load_dwordx4 v[68:71], v[2:3], off
	v_lshl_add_u64 v[0:1], v[76:77], 0, v[0:1]
	global_load_dwordx4 v[72:75], v[0:1], off
	global_load_dwordx4 v[76:79], v[2:3], off offset:64
	ds_read2_b64 v[90:93], v57 offset1:1
	ds_read2_b64 v[80:83], v83 offset1:1
	ds_read2_b64 v[94:97], v84 offset1:1
	ds_read2_b64 v[98:101], v85 offset1:1
	v_mov_b32_e32 v9, v8
	v_mov_b32_e32 v5, v4
	v_mov_b32_e32 v6, v4
	v_mov_b32_e32 v7, v4
	v_mov_b32_e32 v10, v8
	v_mov_b32_e32 v11, v8
	v_mov_b32_e32 v13, v12
	v_mov_b32_e32 v14, v12
	v_mov_b32_e32 v15, v12
	v_mov_b32_e32 v17, v16
	v_mov_b32_e32 v18, v16
	v_mov_b32_e32 v19, v16
	v_mov_b32_e32 v21, v20
	v_mov_b32_e32 v22, v20
	v_mov_b32_e32 v23, v20
	v_mov_b32_e32 v25, v24
	v_mov_b32_e32 v26, v24
	v_mov_b32_e32 v27, v24
	v_mov_b32_e32 v59, v58
	v_mov_b32_e32 v60, v58
	v_mov_b32_e32 v61, v58
	v_mov_b32_e32 v63, v62
	v_mov_b32_e32 v64, v62
	v_mov_b32_e32 v65, v62
	s_waitcnt vmcnt(0) lgkmcnt(0)
	v_mfma_f32_16x16x32_bf16 v[4:7], v[90:93], v[68:71], v[4:7]
	v_mfma_f32_16x16x32_bf16 v[8:11], v[80:83], v[68:71], v[8:11]
	v_mfma_f32_16x16x32_bf16 v[12:15], v[94:97], v[68:71], v[12:15]
	v_mfma_f32_16x16x32_bf16 v[16:19], v[98:101], v[68:71], v[16:19]
	ds_read2_b64 v[68:71], v57 offset0:8 offset1:9
	v_mfma_f32_16x16x32_bf16 v[20:23], v[90:93], v[72:75], v[20:23]
	v_mfma_f32_16x16x32_bf16 v[24:27], v[80:83], v[72:75], v[24:27]
	ds_read2_b64 v[80:83], v87 offset1:1
	v_mfma_f32_16x16x32_bf16 v[58:61], v[94:97], v[72:75], v[58:61]
	v_mfma_f32_16x16x32_bf16 v[62:65], v[98:101], v[72:75], v[62:65]
	ds_read2_b64 v[72:75], v86 offset1:1
	ds_read2_b64 v[84:87], v88 offset1:1
	s_waitcnt lgkmcnt(3)
	v_mfma_f32_16x16x32_bf16 v[4:7], v[68:71], v[76:79], v[4:7]
	s_waitcnt lgkmcnt(1)
	v_mfma_f32_16x16x32_bf16 v[8:11], v[72:75], v[76:79], v[8:11]
	v_mfma_f32_16x16x32_bf16 v[12:15], v[80:83], v[76:79], v[12:15]
	s_waitcnt lgkmcnt(0)
	v_mfma_f32_16x16x32_bf16 v[16:19], v[84:87], v[76:79], v[16:19]
	global_load_dwordx4 v[76:79], v[0:1], off offset:64
	s_waitcnt vmcnt(0) lgkmcnt(0)
	v_mfma_f32_16x16x32_bf16 v[20:23], v[68:71], v[76:79], v[20:23]
	global_load_dwordx4 v[68:71], v[2:3], off offset:128
	v_mfma_f32_16x16x32_bf16 v[24:27], v[72:75], v[76:79], v[24:27]
	ds_read2_b64 v[72:75], v57 offset0:16 offset1:17
	v_mfma_f32_16x16x32_bf16 v[58:61], v[80:83], v[76:79], v[58:61]
	v_mfma_f32_16x16x32_bf16 v[62:65], v[84:87], v[76:79], v[62:65]
	ds_read2_b64 v[76:79], v47 offset1:1
	v_add_u32_e32 v47, 0x2180, v57
	ds_read2_b64 v[80:83], v47 offset1:1
	v_add_u32_e32 v47, 0x3200, v57
	ds_read2_b64 v[84:87], v47 offset1:1
	s_waitcnt vmcnt(0) lgkmcnt(0)
	v_mfma_f32_16x16x32_bf16 v[4:7], v[72:75], v[68:71], v[4:7]
	v_or_b32_e32 v47, s3, v37
	v_mfma_f32_16x16x32_bf16 v[8:11], v[76:79], v[68:71], v[8:11]
	v_mfma_f32_16x16x32_bf16 v[12:15], v[80:83], v[68:71], v[12:15]
	v_mfma_f32_16x16x32_bf16 v[16:19], v[84:87], v[68:71], v[16:19]
	global_load_dwordx4 v[68:71], v[0:1], off offset:128
	s_waitcnt vmcnt(0) lgkmcnt(0)
	v_mfma_f32_16x16x32_bf16 v[58:61], v[80:83], v[68:71], v[58:61]
	global_load_dwordx4 v[80:83], v[2:3], off offset:192
	v_add_u32_e32 v2, 0x1140, v57
	v_mfma_f32_16x16x32_bf16 v[72:75], v[72:75], v[68:71], v[20:23]
	v_mfma_f32_16x16x32_bf16 v[76:79], v[76:79], v[68:71], v[24:27]
	v_mfma_f32_16x16x32_bf16 v[62:65], v[84:87], v[68:71], v[62:65]
	ds_read2_b64 v[68:71], v57 offset0:24 offset1:25
	s_waitcnt vmcnt(0) lgkmcnt(0)
	v_mfma_f32_16x16x32_bf16 v[84:87], v[68:71], v[80:83], v[4:7]
	s_nop 2
	v_add_u32_e32 v6, 0x21c0, v57
	ds_read2_b64 v[2:5], v2 offset1:1
	ds_read2_b64 v[88:91], v6 offset1:1
	v_add_u32_e32 v6, 0x3240, v57
	ds_read2_b64 v[92:95], v6 offset1:1
	s_waitcnt lgkmcnt(2)
	v_mfma_f32_16x16x32_bf16 v[24:27], v[2:5], v[80:83], v[8:11]
	s_waitcnt lgkmcnt(1)
	v_mfma_f32_16x16x32_bf16 v[20:23], v[88:91], v[80:83], v[12:15]
	s_waitcnt lgkmcnt(0)
	v_mfma_f32_16x16x32_bf16 v[16:19], v[92:95], v[80:83], v[16:19]
	global_load_dwordx4 v[80:83], v[0:1], off offset:192
	s_waitcnt vmcnt(0) lgkmcnt(0)
	v_mfma_f32_16x16x32_bf16 v[8:11], v[2:5], v[80:83], v[76:79]
	s_nop 7
	v_pk_add_f32 v[8:9], v[36:37], v[8:9] op_sel_hi:[0,1]
	v_mfma_f32_16x16x32_bf16 v[4:7], v[88:91], v[80:83], v[58:61]
	v_add_f32_e64 v10, v36, v10
	v_add_f32_e64 v11, v36, v11
	s_nop 0
	v_lshlrev_b32_e32 v58, 16, v54
	v_mul_f32_e32 v0, 0x3d372713, v58
	v_mul_f32_e32 v0, v0, v58
	v_mov_b32_e32 v1, v58
	v_fmac_f32_e32 v1, v0, v1
	v_mul_f32_e32 v0, 0x3f4c422a, v1
	v_add_f32_e32 v0, v0, v0
	v_and_b32_e32 v59, 0xffff0000, v54
	v_mul_f32_e32 v0, 0xbfb8aa3b, v0
	v_exp_f32_e32 v56, v0
	v_mul_f32_e32 v0, 0x3d372713, v59
	v_mul_f32_e32 v0, v0, v59
	v_mov_b32_e32 v1, v59
	v_fmac_f32_e32 v1, v0, v1
	v_mul_f32_e32 v0, 0x3f4c422a, v1
	v_add_f32_e32 v0, v0, v0
	v_mul_f32_e32 v0, 0xbfb8aa3b, v0
	v_exp_f32_e32 v57, v0
	v_mfma_f32_16x16x32_bf16 v[0:3], v[92:95], v[80:83], v[62:65]
	v_add_f32_e64 v4, v36, v4
	v_add_f32_e64 v5, v36, v5
	v_pk_add_f32 v[6:7], v[36:37], v[6:7] op_sel_hi:[0,1]
	v_pk_add_f32 v[60:61], v[56:57], 1.0 op_sel_hi:[1,0]
	v_mad_i64_i32 v[56:57], s[0:1], v47, s86, v[32:33]
	v_mfma_f32_16x16x32_bf16 v[12:15], v[68:71], v[80:83], v[72:75]
	v_lshl_add_u64 v[56:57], v[56:57], 0, s[4:5]
	s_nop 0
	v_pk_add_f32 v[0:1], v[36:37], v[0:1] op_sel_hi:[0,1]
	v_rcp_f32_e32 v61, v61
	s_nop 3
	v_pk_add_f32 v[12:13], v[36:37], v[12:13] op_sel_hi:[0,1]
	v_lshlrev_b32_e32 v54, 16, v55
	v_mul_f32_e32 v62, 0x3d372713, v54
	v_mul_f32_e32 v62, v62, v54
	v_mov_b32_e32 v63, v54
	v_and_b32_e32 v55, 0xffff0000, v55
	v_fmac_f32_e32 v63, v62, v63
	v_mul_f32_e32 v62, 0x3f4c422a, v63
	v_mul_f32_e32 v63, 0x3d372713, v55
	v_mul_f32_e32 v63, v63, v55
	v_mov_b32_e32 v68, v55
	v_fmac_f32_e32 v68, v63, v68
	v_mul_f32_e32 v63, 0x3f4c422a, v68
	v_add_f32_e32 v62, v62, v62
	v_add_f32_e32 v63, v63, v63
	v_mul_f32_e32 v62, 0xbfb8aa3b, v62
	v_mul_f32_e32 v63, 0xbfb8aa3b, v63
	v_exp_f32_e32 v62, v62
	v_exp_f32_e32 v63, v63
	v_rcp_f32_e32 v60, v60
	s_nop 0
	v_pk_mul_f32 v[58:59], v[60:61], v[58:59]
	v_pk_add_f32 v[62:63], v[62:63], 1.0 op_sel_hi:[1,0]
	v_pk_add_f32 v[14:15], v[36:37], v[14:15] op_sel_hi:[0,1]
	v_pk_add_f32 v[60:61], v[46:47], v[84:85] op_sel_hi:[0,1]
	v_pk_mul_f32 v[58:59], v[58:59], v[60:61]
	v_pk_add_f32 v[2:3], v[36:37], v[2:3] op_sel_hi:[0,1]
	v_rcp_f32_e32 v61, v63
	v_cvt_pk_bf16_f32 v58, v58, v59
	v_rcp_f32_e32 v60, v62
	s_nop 0
	v_pk_mul_f32 v[54:55], v[60:61], v[54:55]
	v_lshlrev_b32_e32 v60, 16, v52
	v_mul_f32_e32 v47, 0x3d372713, v60
	v_and_b32_e32 v61, 0xffff0000, v52
	v_mul_f32_e32 v47, v47, v60
	v_mov_b32_e32 v52, v60
	v_fmac_f32_e32 v52, v47, v52
	v_mul_f32_e32 v47, 0x3f4c422a, v52
	v_add_f32_e32 v47, v47, v47
	v_mul_f32_e32 v47, 0xbfb8aa3b, v47
	v_exp_f32_e32 v62, v47
	v_mul_f32_e32 v47, 0x3d372713, v61
	v_mul_f32_e32 v47, v47, v61
	v_mov_b32_e32 v52, v61
	v_fmac_f32_e32 v52, v47, v52
	v_mul_f32_e32 v47, 0x3f4c422a, v52
	v_add_f32_e32 v47, v47, v47
	v_mul_f32_e32 v47, 0xbfb8aa3b, v47
	v_exp_f32_e32 v63, v47
	v_pk_add_f32 v[64:65], v[46:47], v[86:87] op_sel_hi:[0,1]
	v_pk_mul_f32 v[54:55], v[54:55], v[64:65]
	v_pk_add_f32 v[62:63], v[62:63], 1.0 op_sel_hi:[1,0]
	s_nop 0
	v_cvt_pk_bf16_f32 v59, v54, v55
	v_lshl_add_u64 v[54:55], v[56:57], 0, v[28:29]
	global_store_dwordx2 v[54:55], v[58:59], off
	v_rcp_f32_e32 v55, v63
	v_lshlrev_b32_e32 v52, 16, v53
	v_mul_f32_e32 v54, 0x3d372713, v52
	v_mul_f32_e32 v54, v54, v52
	v_mov_b32_e32 v58, v52
	v_fmac_f32_e32 v58, v54, v58
	v_mul_f32_e32 v54, 0x3f4c422a, v58
	v_add_f32_e32 v54, v54, v54
	v_and_b32_e32 v53, 0xffff0000, v53
	v_mul_f32_e32 v54, 0xbfb8aa3b, v54
	v_exp_f32_e32 v58, v54
	v_mul_f32_e32 v54, 0x3d372713, v53
	v_mul_f32_e32 v54, v54, v53
	v_mov_b32_e32 v59, v53
	v_fmac_f32_e32 v59, v54, v59
	v_mul_f32_e32 v54, 0x3f4c422a, v59
	v_add_f32_e32 v54, v54, v54
	v_mul_f32_e32 v54, 0xbfb8aa3b, v54
	v_exp_f32_e32 v59, v54
	v_rcp_f32_e32 v54, v62
	s_nop 0
	v_pk_mul_f32 v[54:55], v[54:55], v[60:61]
	v_pk_add_f32 v[58:59], v[58:59], 1.0 op_sel_hi:[1,0]
	s_nop 0
	v_pk_add_f32 v[24:25], v[46:47], v[24:25] op_sel_hi:[0,1]
	v_pk_mul_f32 v[24:25], v[54:55], v[24:25]
	v_rcp_f32_e32 v55, v59
	v_cvt_pk_bf16_f32 v24, v24, v25
	v_rcp_f32_e32 v54, v58
	s_nop 0
	v_pk_mul_f32 v[52:53], v[54:55], v[52:53]
	v_lshlrev_b32_e32 v54, 16, v50
	v_mul_f32_e32 v47, 0x3d372713, v54
	v_and_b32_e32 v55, 0xffff0000, v50
	v_mul_f32_e32 v47, v47, v54
	v_mov_b32_e32 v50, v54
	v_fmac_f32_e32 v50, v47, v50
	v_mul_f32_e32 v47, 0x3f4c422a, v50
	v_add_f32_e32 v47, v47, v47
	v_mul_f32_e32 v47, 0xbfb8aa3b, v47
	v_exp_f32_e32 v58, v47
	v_mul_f32_e32 v47, 0x3d372713, v55
	v_mul_f32_e32 v47, v47, v55
	v_mov_b32_e32 v50, v55
	v_fmac_f32_e32 v50, v47, v50
	v_mul_f32_e32 v47, 0x3f4c422a, v50
	v_add_f32_e32 v47, v47, v47
	v_mul_f32_e32 v47, 0xbfb8aa3b, v47
	v_exp_f32_e32 v59, v47
	v_pk_add_f32 v[26:27], v[46:47], v[26:27] op_sel_hi:[0,1]
	v_pk_mul_f32 v[26:27], v[52:53], v[26:27]
	v_pk_add_f32 v[52:53], v[58:59], 1.0 op_sel_hi:[1,0]
	s_nop 0
	v_cvt_pk_bf16_f32 v25, v26, v27
	v_lshl_add_u64 v[26:27], v[56:57], 0, v[30:31]
	global_store_dwordx2 v[26:27], v[24:25], off
	v_rcp_f32_e32 v25, v53
	v_lshlrev_b32_e32 v26, 16, v51
	v_mul_f32_e32 v50, 0x3d372713, v26
	v_and_b32_e32 v27, 0xffff0000, v51
	v_mul_f32_e32 v50, v50, v26
	v_mov_b32_e32 v51, v26
	v_fmac_f32_e32 v51, v50, v51
	v_mul_f32_e32 v50, 0x3f4c422a, v51
	v_mul_f32_e32 v51, 0x3d372713, v27
	v_mul_f32_e32 v51, v51, v27
	v_mov_b32_e32 v58, v27
	v_fmac_f32_e32 v58, v51, v58
	v_mul_f32_e32 v51, 0x3f4c422a, v58
	v_add_f32_e32 v50, v50, v50
	v_add_f32_e32 v51, v51, v51
	v_mul_f32_e32 v50, 0xbfb8aa3b, v50
	v_mul_f32_e32 v51, 0xbfb8aa3b, v51
	v_exp_f32_e32 v50, v50
	v_exp_f32_e32 v51, v51
	v_rcp_f32_e32 v24, v52
	s_nop 0
	v_pk_mul_f32 v[24:25], v[24:25], v[54:55]
	v_pk_add_f32 v[50:51], v[50:51], 1.0 op_sel_hi:[1,0]
	s_nop 0
	v_pk_add_f32 v[20:21], v[46:47], v[20:21] op_sel_hi:[0,1]
	v_pk_mul_f32 v[20:21], v[24:25], v[20:21]
	v_rcp_f32_e32 v25, v51
	v_cvt_pk_bf16_f32 v20, v20, v21
	v_rcp_f32_e32 v24, v50
	s_nop 0
	v_pk_mul_f32 v[24:25], v[24:25], v[26:27]
	v_lshlrev_b32_e32 v26, 16, v48
	v_mul_f32_e32 v47, 0x3d372713, v26
	v_and_b32_e32 v27, 0xffff0000, v48
	v_mul_f32_e32 v47, v47, v26
	v_mov_b32_e32 v48, v26
	v_fmac_f32_e32 v48, v47, v48
	v_mul_f32_e32 v47, 0x3f4c422a, v48
	v_add_f32_e32 v47, v47, v47
	v_mul_f32_e32 v47, 0xbfb8aa3b, v47
	v_exp_f32_e32 v50, v47
	v_mul_f32_e32 v47, 0x3d372713, v27
	v_mul_f32_e32 v47, v47, v27
	v_mov_b32_e32 v48, v27
	v_fmac_f32_e32 v48, v47, v48
	v_mul_f32_e32 v47, 0x3f4c422a, v48
	v_add_f32_e32 v47, v47, v47
	v_mul_f32_e32 v47, 0xbfb8aa3b, v47
	v_exp_f32_e32 v51, v47
	v_pk_add_f32 v[22:23], v[46:47], v[22:23] op_sel_hi:[0,1]
	v_pk_mul_f32 v[22:23], v[24:25], v[22:23]
	v_pk_add_f32 v[24:25], v[50:51], 1.0 op_sel_hi:[1,0]
	s_nop 0
	v_cvt_pk_bf16_f32 v21, v22, v23
	v_lshl_add_u64 v[22:23], v[56:57], 0, v[34:35]
	global_store_dwordx2 v[22:23], v[20:21], off
	v_rcp_f32_e32 v21, v25
	v_lshlrev_b32_e32 v22, 16, v49
	v_mul_f32_e32 v48, 0x3d372713, v22
	v_and_b32_e32 v23, 0xffff0000, v49
	v_mul_f32_e32 v48, v48, v22
	v_mov_b32_e32 v49, v22
	v_fmac_f32_e32 v49, v48, v49
	v_mul_f32_e32 v48, 0x3f4c422a, v49
	v_mul_f32_e32 v49, 0x3d372713, v23
	v_mul_f32_e32 v49, v49, v23
	v_mov_b32_e32 v50, v23
	v_fmac_f32_e32 v50, v49, v50
	v_mul_f32_e32 v49, 0x3f4c422a, v50
	v_add_f32_e32 v48, v48, v48
	v_add_f32_e32 v49, v49, v49
	v_mul_f32_e32 v48, 0xbfb8aa3b, v48
	v_mul_f32_e32 v49, 0xbfb8aa3b, v49
	v_exp_f32_e32 v48, v48
	v_exp_f32_e32 v49, v49
	v_rcp_f32_e32 v20, v24
	s_nop 0
	v_pk_mul_f32 v[20:21], v[20:21], v[26:27]
	v_pk_add_f32 v[24:25], v[48:49], 1.0 op_sel_hi:[1,0]
	s_nop 0
	v_pk_add_f32 v[16:17], v[46:47], v[16:17] op_sel_hi:[0,1]
	v_pk_mul_f32 v[16:17], v[20:21], v[16:17]
	v_rcp_f32_e32 v21, v25
	v_rcp_f32_e32 v20, v24
	s_nop 0
	v_pk_mul_f32 v[20:21], v[20:21], v[22:23]
	v_pk_add_f32 v[18:19], v[46:47], v[18:19] op_sel_hi:[0,1]
	v_pk_mul_f32 v[18:19], v[20:21], v[18:19]
	v_cvt_pk_bf16_f32 v16, v16, v17
	v_cvt_pk_bf16_f32 v17, v18, v19
	v_lshlrev_b32_e32 v18, 16, v44
	v_mul_f32_e32 v20, 0x3d372713, v18
	v_mul_f32_e32 v20, v20, v18
	v_mov_b32_e32 v21, v18
	v_and_b32_e32 v19, 0xffff0000, v44
	v_fmac_f32_e32 v21, v20, v21
	v_mul_f32_e32 v20, 0x3f4c422a, v21
	v_mul_f32_e32 v21, 0x3d372713, v19
	v_mul_f32_e32 v21, v21, v19
	v_mov_b32_e32 v22, v19
	v_fmac_f32_e32 v22, v21, v22
	v_mul_f32_e32 v21, 0x3f4c422a, v22
	v_add_f32_e32 v20, v20, v20
	v_add_f32_e32 v21, v21, v21
	v_mul_f32_e32 v20, 0xbfb8aa3b, v20
	v_mul_f32_e32 v21, 0xbfb8aa3b, v21
	v_exp_f32_e32 v20, v20
	v_exp_f32_e32 v21, v21
	v_lshl_add_u64 v[22:23], v[56:57], 0, v[66:67]
	global_store_dwordx2 v[22:23], v[16:17], off
	v_or_b32_e32 v16, s2, v37
	v_pk_add_f32 v[20:21], v[20:21], 1.0 op_sel_hi:[1,0]
	v_mad_i64_i32 v[16:17], s[0:1], v16, s86, v[32:33]
	v_lshl_add_u64 v[16:17], v[16:17], 0, s[4:5]
	v_rcp_f32_e32 v21, v21
	v_lshlrev_b32_e32 v22, 16, v45
	v_mul_f32_e32 v24, 0x3d372713, v22
	v_mul_f32_e32 v24, v24, v22
	v_mov_b32_e32 v25, v22
	v_and_b32_e32 v23, 0xffff0000, v45
	v_fmac_f32_e32 v25, v24, v25
	v_mul_f32_e32 v24, 0x3f4c422a, v25
	v_mul_f32_e32 v25, 0x3d372713, v23
	v_mul_f32_e32 v25, v25, v23
	v_mov_b32_e32 v33, v23
	v_fmac_f32_e32 v33, v25, v33
	v_mul_f32_e32 v25, 0x3f4c422a, v33
	v_add_f32_e32 v24, v24, v24
	v_add_f32_e32 v25, v25, v25
	v_mul_f32_e32 v24, 0xbfb8aa3b, v24
	v_mul_f32_e32 v25, 0xbfb8aa3b, v25
	v_exp_f32_e32 v24, v24
	v_exp_f32_e32 v25, v25
	v_rcp_f32_e32 v20, v20
	s_nop 0
	v_pk_mul_f32 v[18:19], v[20:21], v[18:19]
	v_pk_add_f32 v[24:25], v[24:25], 1.0 op_sel_hi:[1,0]
	v_pk_mul_f32 v[12:13], v[18:19], v[12:13]
	s_nop 0
	v_cvt_pk_bf16_f32 v12, v12, v13
	v_rcp_f32_e32 v19, v25
	v_rcp_f32_e32 v18, v24
	v_lshlrev_b32_e32 v20, 16, v42
	v_pk_mul_f32 v[18:19], v[18:19], v[22:23]
	v_mul_f32_e32 v22, 0x3d372713, v20
	v_mul_f32_e32 v22, v22, v20
	v_mov_b32_e32 v23, v20
	v_and_b32_e32 v21, 0xffff0000, v42
	v_fmac_f32_e32 v23, v22, v23
	v_mul_f32_e32 v22, 0x3f4c422a, v23
	v_mul_f32_e32 v23, 0x3d372713, v21
	v_mul_f32_e32 v23, v23, v21
	v_mov_b32_e32 v24, v21
	v_fmac_f32_e32 v24, v23, v24
	v_mul_f32_e32 v23, 0x3f4c422a, v24
	v_add_f32_e32 v22, v22, v22
	v_add_f32_e32 v23, v23, v23
	v_mul_f32_e32 v22, 0xbfb8aa3b, v22
	v_mul_f32_e32 v23, 0xbfb8aa3b, v23
	v_exp_f32_e32 v22, v22
	v_exp_f32_e32 v23, v23
	v_pk_mul_f32 v[14:15], v[18:19], v[14:15]
	v_pk_add_f32 v[18:19], v[22:23], 1.0 op_sel_hi:[1,0]
	s_nop 0
	v_cvt_pk_bf16_f32 v13, v14, v15
	v_lshl_add_u64 v[14:15], v[16:17], 0, v[28:29]
	global_store_dwordx2 v[14:15], v[12:13], off
	v_rcp_f32_e32 v13, v19
	v_lshlrev_b32_e32 v14, 16, v43
	v_mul_f32_e32 v22, 0x3d372713, v14
	v_mul_f32_e32 v22, v22, v14
	v_mov_b32_e32 v23, v14
	v_and_b32_e32 v15, 0xffff0000, v43
	v_fmac_f32_e32 v23, v22, v23
	v_mul_f32_e32 v22, 0x3f4c422a, v23
	v_mul_f32_e32 v23, 0x3d372713, v15
	v_mul_f32_e32 v23, v23, v15
	v_mov_b32_e32 v25, v15
	v_fmac_f32_e32 v25, v23, v25
	v_mul_f32_e32 v23, 0x3f4c422a, v25
	v_add_f32_e32 v22, v22, v22
	v_add_f32_e32 v23, v23, v23
	v_mul_f32_e32 v22, 0xbfb8aa3b, v22
	v_mul_f32_e32 v23, 0xbfb8aa3b, v23
	v_exp_f32_e32 v22, v22
	v_exp_f32_e32 v23, v23
	v_rcp_f32_e32 v12, v18
	s_nop 0
	v_pk_mul_f32 v[12:13], v[12:13], v[20:21]
	v_pk_add_f32 v[18:19], v[22:23], 1.0 op_sel_hi:[1,0]
	v_pk_mul_f32 v[8:9], v[12:13], v[8:9]
	s_nop 0
	v_cvt_pk_bf16_f32 v8, v8, v9
	v_rcp_f32_e32 v13, v19
	v_rcp_f32_e32 v12, v18
	s_nop 0
	v_pk_mul_f32 v[12:13], v[12:13], v[14:15]
	v_lshlrev_b32_e32 v14, 16, v40
	v_mul_f32_e32 v18, 0x3d372713, v14
	v_mul_f32_e32 v18, v18, v14
	v_mov_b32_e32 v19, v14
	v_and_b32_e32 v15, 0xffff0000, v40
	v_fmac_f32_e32 v19, v18, v19
	v_mul_f32_e32 v18, 0x3f4c422a, v19
	v_mul_f32_e32 v19, 0x3d372713, v15
	v_mul_f32_e32 v19, v19, v15
	v_mov_b32_e32 v20, v15
	v_fmac_f32_e32 v20, v19, v20
	v_mul_f32_e32 v19, 0x3f4c422a, v20
	v_add_f32_e32 v18, v18, v18
	v_add_f32_e32 v19, v19, v19
	v_mul_f32_e32 v18, 0xbfb8aa3b, v18
	v_mul_f32_e32 v19, 0xbfb8aa3b, v19
	v_exp_f32_e32 v18, v18
	v_exp_f32_e32 v19, v19
	v_pk_mul_f32 v[10:11], v[12:13], v[10:11]
	v_pk_add_f32 v[12:13], v[18:19], 1.0 op_sel_hi:[1,0]
	s_nop 0
	v_cvt_pk_bf16_f32 v9, v10, v11
	v_lshl_add_u64 v[10:11], v[16:17], 0, v[30:31]
	global_store_dwordx2 v[10:11], v[8:9], off
	v_rcp_f32_e32 v9, v13
	v_lshlrev_b32_e32 v10, 16, v41
	v_mul_f32_e32 v18, 0x3d372713, v10
	v_mul_f32_e32 v18, v18, v10
	v_mov_b32_e32 v19, v10
	v_and_b32_e32 v11, 0xffff0000, v41
	v_fmac_f32_e32 v19, v18, v19
	v_mul_f32_e32 v18, 0x3f4c422a, v19
	v_mul_f32_e32 v19, 0x3d372713, v11
	v_mul_f32_e32 v19, v19, v11
	v_mov_b32_e32 v21, v11
	v_fmac_f32_e32 v21, v19, v21
	v_mul_f32_e32 v19, 0x3f4c422a, v21
	v_add_f32_e32 v18, v18, v18
	v_add_f32_e32 v19, v19, v19
	v_mul_f32_e32 v18, 0xbfb8aa3b, v18
	v_mul_f32_e32 v19, 0xbfb8aa3b, v19
	v_exp_f32_e32 v18, v18
	v_exp_f32_e32 v19, v19
	v_rcp_f32_e32 v8, v12
	s_nop 0
	v_pk_mul_f32 v[8:9], v[8:9], v[14:15]
	v_pk_add_f32 v[12:13], v[18:19], 1.0 op_sel_hi:[1,0]
	v_pk_mul_f32 v[4:5], v[8:9], v[4:5]
	s_nop 0
	v_cvt_pk_bf16_f32 v4, v4, v5
	v_rcp_f32_e32 v9, v13
	v_rcp_f32_e32 v8, v12
	s_nop 0
	v_pk_mul_f32 v[8:9], v[8:9], v[10:11]
	v_lshlrev_b32_e32 v10, 16, v38
	v_mul_f32_e32 v12, 0x3d372713, v10
	v_mul_f32_e32 v12, v12, v10
	v_mov_b32_e32 v13, v10
	v_and_b32_e32 v11, 0xffff0000, v38
	v_fmac_f32_e32 v13, v12, v13
	v_mul_f32_e32 v12, 0x3f4c422a, v13
	v_mul_f32_e32 v13, 0x3d372713, v11
	v_mul_f32_e32 v13, v13, v11
	v_mov_b32_e32 v14, v11
	v_fmac_f32_e32 v14, v13, v14
	v_mul_f32_e32 v13, 0x3f4c422a, v14
	v_add_f32_e32 v12, v12, v12
	v_add_f32_e32 v13, v13, v13
	v_mul_f32_e32 v12, 0xbfb8aa3b, v12
	v_mul_f32_e32 v13, 0xbfb8aa3b, v13
	v_exp_f32_e32 v12, v12
	v_exp_f32_e32 v13, v13
	v_pk_mul_f32 v[6:7], v[8:9], v[6:7]
	v_pk_add_f32 v[8:9], v[12:13], 1.0 op_sel_hi:[1,0]
	s_nop 0
	v_cvt_pk_bf16_f32 v5, v6, v7
	v_lshl_add_u64 v[6:7], v[16:17], 0, v[34:35]
	global_store_dwordx2 v[6:7], v[4:5], off
	v_rcp_f32_e32 v5, v9
	v_lshlrev_b32_e32 v6, 16, v39
	v_mul_f32_e32 v12, 0x3d372713, v6
	v_mul_f32_e32 v12, v12, v6
	v_mov_b32_e32 v13, v6
	v_and_b32_e32 v7, 0xffff0000, v39
	v_fmac_f32_e32 v13, v12, v13
	v_mul_f32_e32 v12, 0x3f4c422a, v13
	v_mul_f32_e32 v13, 0x3d372713, v7
	v_mul_f32_e32 v13, v13, v7
	v_mov_b32_e32 v15, v7
	v_fmac_f32_e32 v15, v13, v15
	v_mul_f32_e32 v13, 0x3f4c422a, v15
	v_add_f32_e32 v12, v12, v12
	v_add_f32_e32 v13, v13, v13
	v_mul_f32_e32 v12, 0xbfb8aa3b, v12
	v_mul_f32_e32 v13, 0xbfb8aa3b, v13
	v_exp_f32_e32 v12, v12
	v_exp_f32_e32 v13, v13
	v_rcp_f32_e32 v4, v8
	s_nop 0
	v_pk_mul_f32 v[4:5], v[4:5], v[10:11]
	v_pk_add_f32 v[8:9], v[12:13], 1.0 op_sel_hi:[1,0]
	v_pk_mul_f32 v[0:1], v[4:5], v[0:1]
	s_nop 0
	v_cvt_pk_bf16_f32 v0, v0, v1
	v_rcp_f32_e32 v5, v9
	v_rcp_f32_e32 v4, v8
	s_nop 0
	v_pk_mul_f32 v[4:5], v[4:5], v[6:7]
	s_nop 0
	v_pk_mul_f32 v[2:3], v[4:5], v[2:3]
	s_nop 0
	v_cvt_pk_bf16_f32 v1, v2, v3
	v_lshl_add_u64 v[2:3], v[16:17], 0, v[66:67]
	global_store_dwordx2 v[2:3], v[0:1], off
	s_waitcnt lgkmcnt(0)
	s_barrier
	v_readlane_b32 s3, v253, 11
	s_lshl_b32 s2, s82, 7
	s_cmp_lt_u32 s3, 0x7c
	s_cbranch_scc1 .Lgmlp_done
	s_cmp_lg_u32 s65, s2
	s_cbranch_scc1 .Lgmlp_restore
	s_sub_i32 s2, s3, 0x7c
	s_lshl_b32 s2, s2, 7
	s_add_i32 s65, s2, 0x4000
	v_writelane_b32 v253, s2, 36
	s_branch .Lgmlp_again
.Lgmlp_restore:
	s_lshl_b32 s2, s3, 7
	s_add_i32 s65, s2, 0x4000
	v_writelane_b32 v253, s2, 36
